# stack: P4 epi counted waits + P5 down epilogue 16 residual loads hoisted + P5 skinny-tile K loop loads software-pipelined 7 k-steps ahead
# baseline (speedup 1.0000x reference)
; __host__ __device__ __forceinline__ size_t img_off(int row, int col, int nkt) { return ((size_t)((row >> 7) * nkt + (col >> 6)) << 14) + (size_t)lds_byte(row & 127, col & 63); }
;     __device__ __forceinline__ void operator()(const f32x4 (&acc)[2][2][4][2], const Unit& u, int wr, int wc, int fr, int fq) const {
;         const int row0 = u.pm * BM + wr * 64 + fr; const int col0 = u.pn * BM + wc * 32 + 8 * fq; const char* x1b = (const char*)(ws + EW_X1B);
; #pragma unroll
;         for (int ai = 0; ai < 2; ++ai)
; #pragma unroll
;             for (int m = 0; m < 4; ++m) { const int row = row0 + ai * HALF + m * 16; const size_t off = (size_t)row * 1024 + col0;
; #pragma unroll
;                 for (int bj = 0; bj < 2; ++bj) { const u32x4 xb = __builtin_nontemporal_load((const u32x4*)(x1b + img_off(row, col0 + bj * HALF, 16))); float* p = y + off + bj * HALF;
;                     const f32x4 x0 = (f32x4){__builtin_bit_cast(float, xb.x << 16), __builtin_bit_cast(float, xb.x & 0xffff0000u), __builtin_bit_cast(float, xb.y << 16), __builtin_bit_cast(float, xb.y & 0xffff0000u)};
;                     const f32x4 x1 = (f32x4){__builtin_bit_cast(float, xb.z << 16), __builtin_bit_cast(float, xb.z & 0xffff0000u), __builtin_bit_cast(float, xb.w << 16), __builtin_bit_cast(float, xb.w & 0xffff0000u)};
;                     __builtin_nontemporal_store(acc[ai][bj][m][0] + x0, (f32x4*)p); __builtin_nontemporal_store(acc[ai][bj][m][1] + x1, (f32x4*)(p + 4)); } }
.LBB0_1427:
	s_lshl_b32 s13, s56, 8
	s_lshl_b32 s12, s55, 8
	s_or_b32 s13, s13, s45
	s_add_i32 s12, s12, s44
	v_or_b32_e32 v138, s13, v141
	v_or_b32_e32 v136, s12, v140
	v_lshlrev_b32_e32 v130, 1, v138
	s_bfe_u32 s55, s45, 0x10005
	v_and_b32_e32 v146, 48, v130
	s_ashr_i32 s12, s12, 3
	v_lshlrev_b32_e32 v130, 6, v136
	s_and_b32 s36, s12, -16
	s_ashr_i32 s57, s13, 6
	s_or_b32 s37, s55, s49
	v_and_or_b32 v147, v130, s48, v146
	v_lshlrev_b32_e32 v130, 2, v136
	s_add_i32 s12, s36, s57
	s_lshl_b32 s58, s37, 10
	v_and_b32_e32 v160, 32, v130
	s_ashr_i32 s13, s12, 31
	v_bitop3_b32 v130, v147, s58, v160 bitop3:0xde
	s_lshl_b64 s[12:13], s[12:13], 14
	v_lshl_add_u64 v[152:153], s[30:31], 0, v[130:131]
	v_lshl_add_u64 v[148:149], v[152:153], 0, s[12:13]
	s_mov_b64 s[98:99], 0x1000
	s_mov_b64 s[100:101], 0x8000
	v_lshl_add_u64 v[230:231], v[148:149], 0, s[98:99]
	v_lshl_add_u64 v[232:233], v[148:149], 0, s[100:101]
	v_lshl_add_u64 v[234:235], v[230:231], 0, s[100:101]
	s_mov_b64 s[100:101], 0x40000
	v_lshl_add_u64 v[236:237], v[148:149], 0, s[100:101]
	v_lshl_add_u64 v[238:239], v[230:231], 0, s[100:101]
	v_lshl_add_u64 v[240:241], v[232:233], 0, s[100:101]
	v_lshl_add_u64 v[242:243], v[234:235], 0, s[100:101]
	global_load_dwordx4 v[162:165], v[148:149], off nt
	global_load_dwordx4 v[166:169], v[232:233], off nt
	global_load_dwordx4 v[170:173], v[148:149], off offset:2048 nt
	global_load_dwordx4 v[174:177], v[232:233], off offset:2048 nt
	global_load_dwordx4 v[178:181], v[230:231], off nt
	global_load_dwordx4 v[182:185], v[234:235], off nt
	global_load_dwordx4 v[186:189], v[230:231], off offset:2048 nt
	global_load_dwordx4 v[190:193], v[234:235], off offset:2048 nt
	global_load_dwordx4 v[194:197], v[236:237], off nt
	global_load_dwordx4 v[202:205], v[240:241], off nt
	global_load_dwordx4 v[206:209], v[236:237], off offset:2048 nt
	global_load_dwordx4 v[210:213], v[240:241], off offset:2048 nt
	global_load_dwordx4 v[214:217], v[238:239], off nt
	global_load_dwordx4 v[218:221], v[242:243], off nt
	global_load_dwordx4 v[222:225], v[238:239], off offset:2048 nt
	global_load_dwordx4 v[226:229], v[242:243], off offset:2048 nt
	v_readlane_b32 s60, v251, 6
	v_ashrrev_i32_e32 v137, 31, v136
	s_or_b32 s56, s57, 2
	v_readlane_b32 s62, v251, 8
	v_readlane_b32 s63, v251, 9
	v_readlane_b32 s66, v251, 12
	v_readlane_b32 s67, v251, 13
	v_ashrrev_i32_e32 v139, 31, v138
	v_lshlrev_b64 v[154:155], 12, v[136:137]
	s_add_i32 s36, s36, s56
	s_mov_b64 s[62:63], s[66:67]
	v_lshlrev_b64 v[138:139], 2, v[138:139]
	v_lshl_add_u64 v[154:155], s[62:63], 0, v[154:155]
	s_ashr_i32 s37, s36, 31
	v_lshl_add_u64 v[154:155], v[154:155], 0, v[138:139]
	s_lshl_b64 s[36:37], s[36:37], 14
	v_lshl_add_u64 v[152:153], v[152:153], 0, s[36:37]
	s_and_b64 vcc, exec, s[0:1]
	s_mov_b64 s[0:1], -1
	v_readlane_b32 s61, v251, 7
	v_readlane_b32 s64, v251, 10
	v_readlane_b32 s65, v251, 11
	s_waitcnt vmcnt(15)
	v_lshlrev_b32_e32 v156, 16, v162
	v_and_b32_e32 v157, 0xffff0000, v162
	v_lshlrev_b32_e32 v148, 16, v163
	v_and_b32_e32 v149, 0xffff0000, v163
	v_lshlrev_b32_e32 v158, 16, v164
	v_and_b32_e32 v159, 0xffff0000, v164
	v_lshlrev_b32_e32 v150, 16, v165
	v_and_b32_e32 v151, 0xffff0000, v165
	v_pk_add_f32 v[126:127], v[126:127], v[148:149]
	v_pk_add_f32 v[124:125], v[124:125], v[156:157]
	v_pk_add_f32 v[122:123], v[122:123], v[150:151]
	v_pk_add_f32 v[120:121], v[120:121], v[158:159]
	global_store_dwordx4 v[154:155], v[124:127], off nt
	global_store_dwordx4 v[154:155], v[120:123], off offset:16 nt
	s_nop 0
	v_or_b32_e32 v124, 16, v136
	v_lshrrev_b32_e32 v125, 3, v124
	v_and_or_b32 v125, v125, 10, s55
	v_lshlrev_b32_e32 v125, 10, v125
	v_bitop3_b32 v130, v147, v125, v160 bitop3:0xde
	v_lshl_add_u64 v[126:127], s[30:31], 0, v[130:131]
	v_lshl_add_u64 v[148:149], v[126:127], 0, s[12:13]
	v_ashrrev_i32_e32 v125, 31, v124
	s_waitcnt vmcnt(16)
	v_lshlrev_b32_e32 v150, 16, v166
	v_and_b32_e32 v151, 0xffff0000, v166
	v_lshlrev_b32_e32 v120, 16, v167
	v_and_b32_e32 v121, 0xffff0000, v167
	v_lshlrev_b32_e32 v152, 16, v168
	v_and_b32_e32 v153, 0xffff0000, v168
	v_lshlrev_b32_e32 v122, 16, v169
	v_and_b32_e32 v123, 0xffff0000, v169
	v_pk_add_f32 v[118:119], v[118:119], v[120:121]
	v_pk_add_f32 v[116:117], v[116:117], v[150:151]
	v_pk_add_f32 v[114:115], v[114:115], v[122:123]
	v_pk_add_f32 v[112:113], v[112:113], v[152:153]
	global_store_dwordx4 v[154:155], v[116:119], off offset:512 nt
	global_store_dwordx4 v[154:155], v[112:115], off offset:528 nt
	s_nop 0
	v_lshlrev_b64 v[116:117], 12, v[124:125]
	v_lshl_add_u64 v[116:117], s[62:63], 0, v[116:117]
	v_lshl_add_u64 v[116:117], v[116:117], 0, v[138:139]
	v_lshl_add_u64 v[118:119], v[126:127], 0, s[36:37]
	s_waitcnt vmcnt(17)
	v_lshlrev_b32_e32 v120, 16, v170
	v_and_b32_e32 v121, 0xffff0000, v170
	v_lshlrev_b32_e32 v112, 16, v171
	v_and_b32_e32 v113, 0xffff0000, v171
	v_lshlrev_b32_e32 v122, 16, v172
	v_and_b32_e32 v123, 0xffff0000, v172
	v_lshlrev_b32_e32 v114, 16, v173
	v_and_b32_e32 v115, 0xffff0000, v173
	v_pk_add_f32 v[110:111], v[110:111], v[112:113]
	v_pk_add_f32 v[108:109], v[108:109], v[120:121]
	v_pk_add_f32 v[106:107], v[106:107], v[114:115]
	v_pk_add_f32 v[104:105], v[104:105], v[122:123]
	global_store_dwordx4 v[116:117], v[108:111], off nt
	global_store_dwordx4 v[116:117], v[104:107], off offset:16 nt
	s_nop 0
	v_or_b32_e32 v108, 32, v136
	v_lshrrev_b32_e32 v109, 3, v108
	v_and_or_b32 v109, v109, 12, s55
	v_lshlrev_b32_e32 v109, 10, v109
	v_bitop3_b32 v130, v147, v109, v160 bitop3:0xde
	v_lshl_add_u64 v[110:111], s[30:31], 0, v[130:131]
	v_lshl_add_u64 v[112:113], v[110:111], 0, s[12:13]
	v_ashrrev_i32_e32 v109, 31, v108
	s_waitcnt vmcnt(18)
; __host__ __device__ __forceinline__ size_t img_off(int row, int col, int nkt) { return ((size_t)((row >> 7) * nkt + (col >> 6)) << 14) + (size_t)lds_byte(row & 127, col & 63); }
;     __device__ __forceinline__ void operator()(const f32x4 (&acc)[2][2][4][2], const Unit& u, int wr, int wc, int fr, int fq) const {
;     ...
;             for (int m = 0; m < 4; ++m) { const int row = row0 + ai * HALF + m * 16; const size_t off = (size_t)row * 1024 + col0;
; #pragma unroll
;                 for (int bj = 0; bj < 2; ++bj) { const u32x4 xb = __builtin_nontemporal_load((const u32x4*)(x1b + img_off(row, col0 + bj * HALF, 16))); float* p = y + off + bj * HALF;
;                     const f32x4 x0 = (f32x4){__builtin_bit_cast(float, xb.x << 16), __builtin_bit_cast(float, xb.x & 0xffff0000u), __builtin_bit_cast(float, xb.y << 16), __builtin_bit_cast(float, xb.y & 0xffff0000u)};
;                     const f32x4 x1 = (f32x4){__builtin_bit_cast(float, xb.z << 16), __builtin_bit_cast(float, xb.z & 0xffff0000u), __builtin_bit_cast(float, xb.w << 16), __builtin_bit_cast(float, xb.w & 0xffff0000u)};
;                     __builtin_nontemporal_store(acc[ai][bj][m][0] + x0, (f32x4*)p); __builtin_nontemporal_store(acc[ai][bj][m][1] + x1, (f32x4*)(p + 4)); } }
	v_lshlrev_b32_e32 v114, 16, v174
	v_and_b32_e32 v115, 0xffff0000, v174
	v_lshlrev_b32_e32 v104, 16, v175
	v_and_b32_e32 v105, 0xffff0000, v175
	v_lshlrev_b32_e32 v118, 16, v176
	v_and_b32_e32 v119, 0xffff0000, v176
	v_lshlrev_b32_e32 v106, 16, v177
	v_and_b32_e32 v107, 0xffff0000, v177
	v_pk_add_f32 v[102:103], v[102:103], v[104:105]
	v_pk_add_f32 v[100:101], v[100:101], v[114:115]
	v_pk_add_f32 v[98:99], v[98:99], v[106:107]
	v_pk_add_f32 v[96:97], v[96:97], v[118:119]
	global_store_dwordx4 v[116:117], v[100:103], off offset:512 nt
	global_store_dwordx4 v[116:117], v[96:99], off offset:528 nt
	s_nop 0
	v_lshlrev_b64 v[100:101], 12, v[108:109]
	v_lshl_add_u64 v[100:101], s[62:63], 0, v[100:101]
	v_lshl_add_u64 v[100:101], v[100:101], 0, v[138:139]
	v_lshl_add_u64 v[102:103], v[110:111], 0, s[36:37]
	s_waitcnt vmcnt(19)
	v_lshlrev_b32_e32 v104, 16, v178
	v_and_b32_e32 v105, 0xffff0000, v178
	v_lshlrev_b32_e32 v96, 16, v179
	v_and_b32_e32 v97, 0xffff0000, v179
	v_lshlrev_b32_e32 v106, 16, v180
	v_and_b32_e32 v107, 0xffff0000, v180
	v_lshlrev_b32_e32 v98, 16, v181
	v_and_b32_e32 v99, 0xffff0000, v181
	v_pk_add_f32 v[94:95], v[94:95], v[96:97]
	v_pk_add_f32 v[92:93], v[92:93], v[104:105]
	v_pk_add_f32 v[90:91], v[90:91], v[98:99]
	v_pk_add_f32 v[88:89], v[88:89], v[106:107]
	global_store_dwordx4 v[100:101], v[92:95], off nt
	global_store_dwordx4 v[100:101], v[88:91], off offset:16 nt
	s_nop 0
	v_or_b32_e32 v92, 48, v136
	v_lshrrev_b32_e32 v93, 3, v92
	v_and_or_b32 v93, v93, 14, s55
	v_lshlrev_b32_e32 v93, 10, v93
	v_bitop3_b32 v130, v147, v93, v160 bitop3:0xde
	v_lshl_add_u64 v[94:95], s[30:31], 0, v[130:131]
	v_lshl_add_u64 v[96:97], v[94:95], 0, s[12:13]
	v_ashrrev_i32_e32 v93, 31, v92
	s_waitcnt vmcnt(20)
	v_lshlrev_b32_e32 v98, 16, v182
	v_and_b32_e32 v99, 0xffff0000, v182
	v_lshlrev_b32_e32 v88, 16, v183
	v_and_b32_e32 v89, 0xffff0000, v183
	v_lshlrev_b32_e32 v102, 16, v184
	v_and_b32_e32 v103, 0xffff0000, v184
	v_lshlrev_b32_e32 v90, 16, v185
	v_and_b32_e32 v91, 0xffff0000, v185
	v_pk_add_f32 v[86:87], v[86:87], v[88:89]
	v_pk_add_f32 v[84:85], v[84:85], v[98:99]
	v_pk_add_f32 v[82:83], v[82:83], v[90:91]
	v_pk_add_f32 v[80:81], v[80:81], v[102:103]
	global_store_dwordx4 v[100:101], v[84:87], off offset:512 nt
	global_store_dwordx4 v[100:101], v[80:83], off offset:528 nt
	s_nop 0
	v_lshlrev_b64 v[84:85], 12, v[92:93]
	v_lshl_add_u64 v[84:85], s[62:63], 0, v[84:85]
	v_lshl_add_u64 v[84:85], v[84:85], 0, v[138:139]
	v_lshl_add_u64 v[86:87], v[94:95], 0, s[36:37]
	s_waitcnt vmcnt(21)
	v_lshlrev_b32_e32 v88, 16, v186
	v_and_b32_e32 v89, 0xffff0000, v186
	v_lshlrev_b32_e32 v80, 16, v187
	v_and_b32_e32 v81, 0xffff0000, v187
	v_lshlrev_b32_e32 v90, 16, v188
	v_and_b32_e32 v91, 0xffff0000, v188
	v_lshlrev_b32_e32 v82, 16, v189
	v_and_b32_e32 v83, 0xffff0000, v189
	v_pk_add_f32 v[78:79], v[78:79], v[80:81]
	v_pk_add_f32 v[76:77], v[76:77], v[88:89]
	v_pk_add_f32 v[74:75], v[74:75], v[82:83]
	v_pk_add_f32 v[72:73], v[72:73], v[90:91]
	global_store_dwordx4 v[84:85], v[76:79], off nt
	global_store_dwordx4 v[84:85], v[72:75], off offset:16 nt
	s_nop 0
	v_add_u32_e32 v78, 0x80, v136
	v_ashrrev_i32_e32 v72, 3, v78
	v_lshlrev_b32_e32 v73, 6, v78
	v_lshlrev_b32_e32 v79, 2, v78
	v_and_b32_e32 v90, -16, v72
	v_and_or_b32 v80, v73, s48, v146
	v_and_b32_e32 v79, 32, v79
	v_add_u32_e32 v72, s57, v90
	v_ashrrev_i32_e32 v73, 31, v72
	v_bitop3_b32 v130, v80, s58, v79 bitop3:0xde
	v_lshlrev_b64 v[72:73], 14, v[72:73]
	v_lshl_add_u64 v[80:81], s[30:31], 0, v[130:131]
	v_lshl_add_u64 v[82:83], v[80:81], 0, v[72:73]
	v_ashrrev_i32_e32 v79, 31, v78
	s_waitcnt vmcnt(22)
	v_lshlrev_b32_e32 v86, 16, v190
	v_and_b32_e32 v87, 0xffff0000, v190
	v_lshlrev_b32_e32 v74, 16, v191
	v_and_b32_e32 v75, 0xffff0000, v191
	v_lshlrev_b32_e32 v88, 16, v192
	v_and_b32_e32 v89, 0xffff0000, v192
	v_lshlrev_b32_e32 v76, 16, v193
	v_and_b32_e32 v77, 0xffff0000, v193
	v_pk_add_f32 v[70:71], v[70:71], v[74:75]
	v_pk_add_f32 v[68:69], v[68:69], v[86:87]
	v_pk_add_f32 v[66:67], v[66:67], v[76:77]
	v_pk_add_f32 v[64:65], v[64:65], v[88:89]
	global_store_dwordx4 v[84:85], v[68:71], off offset:512 nt
	global_store_dwordx4 v[84:85], v[64:67], off offset:528 nt
	s_nop 0
	v_add_u32_e32 v70, s56, v90
	v_lshlrev_b64 v[64:65], 12, v[78:79]
	v_lshl_add_u64 v[64:65], s[62:63], 0, v[64:65]
	v_ashrrev_i32_e32 v71, 31, v70
	v_lshl_add_u64 v[74:75], v[64:65], 0, v[138:139]
	v_lshlrev_b64 v[64:65], 14, v[70:71]
	v_lshl_add_u64 v[70:71], v[80:81], 0, v[64:65]
	s_waitcnt vmcnt(23)
	v_lshlrev_b32_e32 v76, 16, v194
	v_and_b32_e32 v77, 0xffff0000, v194
	v_lshlrev_b32_e32 v66, 16, v195
	v_and_b32_e32 v67, 0xffff0000, v195
	v_lshlrev_b32_e32 v78, 16, v196
	v_and_b32_e32 v79, 0xffff0000, v196
	v_lshlrev_b32_e32 v68, 16, v197
	v_and_b32_e32 v69, 0xffff0000, v197
	v_pk_add_f32 v[62:63], v[62:63], v[66:67]
	v_pk_add_f32 v[60:61], v[60:61], v[76:77]
	v_pk_add_f32 v[58:59], v[58:59], v[68:69]
	v_pk_add_f32 v[56:57], v[56:57], v[78:79]
	global_store_dwordx4 v[74:75], v[60:63], off nt
	global_store_dwordx4 v[74:75], v[56:59], off offset:16 nt
	s_nop 0
	v_add_u32_e32 v60, 0x90, v136
	v_lshrrev_b32_e32 v61, 3, v60
	v_lshlrev_b32_e32 v62, 6, v60
	v_lshlrev_b32_e32 v63, 2, v60
	v_and_or_b32 v61, v61, 10, s55
	v_and_or_b32 v62, v62, s48, v146
	v_and_b32_e32 v63, 32, v63
	v_lshlrev_b32_e32 v61, 10, v61
	v_bitop3_b32 v130, v62, v61, v63 bitop3:0xde
	v_lshl_add_u64 v[62:63], s[30:31], 0, v[130:131]
	v_lshl_add_u64 v[66:67], v[62:63], 0, v[72:73]
	v_ashrrev_i32_e32 v61, 31, v60
	s_waitcnt vmcnt(24)
; __host__ __device__ __forceinline__ size_t img_off(int row, int col, int nkt) { return ((size_t)((row >> 7) * nkt + (col >> 6)) << 14) + (size_t)lds_byte(row & 127, col & 63); }
; #define PG8_BAR __builtin_amdgcn_s_barrier()
;     __device__ __forceinline__ void operator()(const f32x4 (&acc)[2][2][4][2], const Unit& u, int wr, int wc, int fr, int fq) const {
;     ...
;             for (int m = 0; m < 4; ++m) { const int row = row0 + ai * HALF + m * 16; const size_t off = (size_t)row * 1024 + col0;
; #pragma unroll
;                 for (int bj = 0; bj < 2; ++bj) { const u32x4 xb = __builtin_nontemporal_load((const u32x4*)(x1b + img_off(row, col0 + bj * HALF, 16))); float* p = y + off + bj * HALF;
;                     const f32x4 x0 = (f32x4){__builtin_bit_cast(float, xb.x << 16), __builtin_bit_cast(float, xb.x & 0xffff0000u), __builtin_bit_cast(float, xb.y << 16), __builtin_bit_cast(float, xb.y & 0xffff0000u)};
;                     const f32x4 x1 = (f32x4){__builtin_bit_cast(float, xb.z << 16), __builtin_bit_cast(float, xb.z & 0xffff0000u), __builtin_bit_cast(float, xb.w << 16), __builtin_bit_cast(float, xb.w & 0xffff0000u)};
;                     __builtin_nontemporal_store(acc[ai][bj][m][0] + x0, (f32x4*)p); __builtin_nontemporal_store(acc[ai][bj][m][1] + x1, (f32x4*)(p + 4)); } }
; template <class Epi, class Sched, bool ALIGN_EPI = false, bool SP2 = false>
; __device__ __forceinline__ void gemm_phase(PG8_LAS unsigned char* lds, const Gemm g, const Sched& S, const Epi& E) {
;     ...
;         if (!has_next) break;
; #pragma unroll
;         for (int a = 0; a < 2; ++a)
; #pragma unroll
;             for (int b = 0; b < 2; ++b)
; #pragma unroll
;                 for (int m = 0; m < 4; ++m)
; #pragma unroll
;                     for (int n = 0; n < 2; ++n) acc[a][b][m][n] = (f32x4){0.f, 0.f, 0.f, 0.f};
;         cur = nxt; cA = nA; cB = nB; ++ui;
;         if constexpr (ALIGN_EPI) { if (wr == 1) PG8_BAR; }
;     }
	v_lshlrev_b32_e32 v68, 16, v202
	v_and_b32_e32 v69, 0xffff0000, v202
	v_lshlrev_b32_e32 v56, 16, v203
	v_and_b32_e32 v57, 0xffff0000, v203
	v_lshlrev_b32_e32 v70, 16, v204
	v_and_b32_e32 v71, 0xffff0000, v204
	v_lshlrev_b32_e32 v58, 16, v205
	v_and_b32_e32 v59, 0xffff0000, v205
	v_pk_add_f32 v[54:55], v[54:55], v[56:57]
	v_pk_add_f32 v[52:53], v[52:53], v[68:69]
	v_pk_add_f32 v[50:51], v[50:51], v[58:59]
	v_pk_add_f32 v[48:49], v[48:49], v[70:71]
	global_store_dwordx4 v[74:75], v[52:55], off offset:512 nt
	global_store_dwordx4 v[74:75], v[48:51], off offset:528 nt
	s_nop 0
	v_lshlrev_b64 v[52:53], 12, v[60:61]
	v_lshl_add_u64 v[52:53], s[62:63], 0, v[52:53]
	v_lshl_add_u64 v[52:53], v[52:53], 0, v[138:139]
	v_lshl_add_u64 v[54:55], v[62:63], 0, v[64:65]
	s_waitcnt vmcnt(25)
	v_lshlrev_b32_e32 v56, 16, v206
	v_and_b32_e32 v57, 0xffff0000, v206
	v_lshlrev_b32_e32 v48, 16, v207
	v_and_b32_e32 v49, 0xffff0000, v207
	v_lshlrev_b32_e32 v58, 16, v208
	v_and_b32_e32 v59, 0xffff0000, v208
	v_lshlrev_b32_e32 v50, 16, v209
	v_and_b32_e32 v51, 0xffff0000, v209
	v_pk_add_f32 v[46:47], v[46:47], v[48:49]
	v_pk_add_f32 v[44:45], v[44:45], v[56:57]
	v_pk_add_f32 v[42:43], v[42:43], v[50:51]
	v_pk_add_f32 v[40:41], v[40:41], v[58:59]
	global_store_dwordx4 v[52:53], v[44:47], off nt
	global_store_dwordx4 v[52:53], v[40:43], off offset:16 nt
	s_nop 0
	v_add_u32_e32 v44, 0xa0, v136
	v_lshrrev_b32_e32 v45, 3, v44
	v_lshlrev_b32_e32 v46, 6, v44
	v_lshlrev_b32_e32 v47, 2, v44
	v_and_or_b32 v45, v45, 12, s55
	v_and_or_b32 v46, v46, s48, v146
	v_and_b32_e32 v47, 32, v47
	v_lshlrev_b32_e32 v45, 10, v45
	v_bitop3_b32 v130, v46, v45, v47 bitop3:0xde
	v_lshl_add_u64 v[46:47], s[30:31], 0, v[130:131]
	v_lshl_add_u64 v[48:49], v[46:47], 0, v[72:73]
	v_ashrrev_i32_e32 v45, 31, v44
	s_waitcnt vmcnt(26)
	v_lshlrev_b32_e32 v50, 16, v210
	v_and_b32_e32 v51, 0xffff0000, v210
	v_lshlrev_b32_e32 v40, 16, v211
	v_and_b32_e32 v41, 0xffff0000, v211
	v_lshlrev_b32_e32 v54, 16, v212
	v_and_b32_e32 v55, 0xffff0000, v212
	v_lshlrev_b32_e32 v42, 16, v213
	v_and_b32_e32 v43, 0xffff0000, v213
	v_pk_add_f32 v[38:39], v[38:39], v[40:41]
	v_pk_add_f32 v[36:37], v[36:37], v[50:51]
	v_pk_add_f32 v[34:35], v[34:35], v[42:43]
	v_pk_add_f32 v[32:33], v[32:33], v[54:55]
	global_store_dwordx4 v[52:53], v[36:39], off offset:512 nt
	global_store_dwordx4 v[52:53], v[32:35], off offset:528 nt
	s_nop 0
	v_lshlrev_b64 v[36:37], 12, v[44:45]
	v_lshl_add_u64 v[36:37], s[62:63], 0, v[36:37]
	v_lshl_add_u64 v[36:37], v[36:37], 0, v[138:139]
	v_lshl_add_u64 v[38:39], v[46:47], 0, v[64:65]
	s_waitcnt vmcnt(27)
	v_lshlrev_b32_e32 v40, 16, v214
	v_and_b32_e32 v41, 0xffff0000, v214
	v_lshlrev_b32_e32 v32, 16, v215
	v_and_b32_e32 v33, 0xffff0000, v215
	v_lshlrev_b32_e32 v42, 16, v216
	v_and_b32_e32 v43, 0xffff0000, v216
	v_lshlrev_b32_e32 v34, 16, v217
	v_and_b32_e32 v35, 0xffff0000, v217
	v_pk_add_f32 v[30:31], v[30:31], v[32:33]
	v_pk_add_f32 v[28:29], v[28:29], v[40:41]
	v_pk_add_f32 v[26:27], v[26:27], v[34:35]
	v_pk_add_f32 v[24:25], v[24:25], v[42:43]
	global_store_dwordx4 v[36:37], v[28:31], off nt
	global_store_dwordx4 v[36:37], v[24:27], off offset:16 nt
	s_nop 0
	v_add_u32_e32 v28, 0xb0, v136
	v_lshrrev_b32_e32 v29, 3, v28
	v_lshlrev_b32_e32 v30, 6, v28
	v_lshlrev_b32_e32 v31, 2, v28
	v_and_or_b32 v29, v29, 14, s55
	v_and_or_b32 v30, v30, s48, v146
	v_and_b32_e32 v31, 32, v31
	v_lshlrev_b32_e32 v29, 10, v29
	v_bitop3_b32 v130, v30, v29, v31 bitop3:0xde
	v_lshl_add_u64 v[30:31], s[30:31], 0, v[130:131]
	v_lshl_add_u64 v[32:33], v[30:31], 0, v[72:73]
	v_ashrrev_i32_e32 v29, 31, v28
	s_waitcnt vmcnt(28)
	v_lshlrev_b32_e32 v34, 16, v218
	v_and_b32_e32 v35, 0xffff0000, v218
	v_lshlrev_b32_e32 v24, 16, v219
	v_and_b32_e32 v25, 0xffff0000, v219
	v_lshlrev_b32_e32 v38, 16, v220
	v_and_b32_e32 v39, 0xffff0000, v220
	v_lshlrev_b32_e32 v26, 16, v221
	v_and_b32_e32 v27, 0xffff0000, v221
	v_pk_add_f32 v[22:23], v[22:23], v[24:25]
	v_pk_add_f32 v[20:21], v[20:21], v[34:35]
	v_pk_add_f32 v[18:19], v[18:19], v[26:27]
	v_pk_add_f32 v[16:17], v[16:17], v[38:39]
	global_store_dwordx4 v[36:37], v[20:23], off offset:512 nt
	global_store_dwordx4 v[36:37], v[16:19], off offset:528 nt
	s_nop 0
	v_lshlrev_b64 v[20:21], 12, v[28:29]
	v_lshl_add_u64 v[20:21], s[62:63], 0, v[20:21]
	v_lshl_add_u64 v[20:21], v[20:21], 0, v[138:139]
	v_lshl_add_u64 v[22:23], v[30:31], 0, v[64:65]
	s_waitcnt vmcnt(29)
	v_lshlrev_b32_e32 v24, 16, v222
	v_and_b32_e32 v25, 0xffff0000, v222
	v_lshlrev_b32_e32 v16, 16, v223
	v_and_b32_e32 v17, 0xffff0000, v223
	v_lshlrev_b32_e32 v26, 16, v224
	v_and_b32_e32 v27, 0xffff0000, v224
	v_lshlrev_b32_e32 v18, 16, v225
	v_and_b32_e32 v19, 0xffff0000, v225
	v_pk_add_f32 v[14:15], v[14:15], v[16:17]
	v_pk_add_f32 v[12:13], v[12:13], v[24:25]
	v_pk_add_f32 v[10:11], v[10:11], v[18:19]
	v_pk_add_f32 v[8:9], v[8:9], v[26:27]
	global_store_dwordx4 v[20:21], v[12:15], off nt
	global_store_dwordx4 v[20:21], v[8:11], off offset:16 nt
	s_nop 0
	s_waitcnt vmcnt(30)
	v_lshlrev_b32_e32 v12, 16, v226
	v_and_b32_e32 v13, 0xffff0000, v226
	v_lshlrev_b32_e32 v8, 16, v227
	v_and_b32_e32 v9, 0xffff0000, v227
	v_lshlrev_b32_e32 v14, 16, v228
	v_and_b32_e32 v15, 0xffff0000, v228
	v_lshlrev_b32_e32 v10, 16, v229
	v_and_b32_e32 v11, 0xffff0000, v229
	v_pk_add_f32 v[6:7], v[6:7], v[8:9]
	v_pk_add_f32 v[4:5], v[4:5], v[12:13]
	v_pk_add_f32 v[2:3], v[2:3], v[10:11]
	v_pk_add_f32 v[0:1], v[0:1], v[14:15]
	global_store_dwordx4 v[20:21], v[4:7], off offset:512 nt
	global_store_dwordx4 v[20:21], v[0:3], off offset:528 nt
	s_cbranch_vccnz .LBB0_1412
	s_andn2_b64 vcc, exec, s[18:19]
	s_cbranch_vccnz .LBB0_1411
	s_barrier
	s_branch .LBB0_1411

; __host__ __device__ __forceinline__ size_t img_off(int row, int col, int nkt) { return ((size_t)((row >> 7) * nkt + (col >> 6)) << 14) + (size_t)lds_byte(row & 127, col & 63); }
; __host__ __device__ __forceinline__ size_t img_off_b(int row, int col, int nkt) { return img_off((row & ~31) | invperm32(row & 31), col, nkt); }
; template <int K, int MODE>
; __device__ __forceinline__ void skinny_tile(Frame& F, const Args& A, const bf16* Am  , const bf16* Bt  ) {
;     ...
;     constexpr int KW = K / 8, NK = KW / 16;
;     const char* ab = (const char*)Am; const char* bb = (const char*)Bt; const int arow = MP + r0 + il, brow = c0 + il, kc0 = w * KW + 8 * hi;
;     f32x16 acc0, acc1;
; #pragma unroll
;     for (int q = 0; q < 16; ++q) { acc0[q] = 0.f; acc1[q] = 0.f; }
;     constexpr int CH = (NK % 8 == 0) ? 8 : 11;
;     static_assert(NK % CH == 0, "skinny_tile: K slice");
; #pragma unroll 1
;     for (int k0 = 0; k0 < NK; k0 += CH) {
;         bf16x8 bf[CH], a0[CH], a1[CH];
; #pragma unroll
;         for (int c = 0; c < CH; ++c) { const int kc = kc0 + 16 * (k0 + c); bf[c] = *(const bf16x8*)(bb + pg8::img_off_b(brow, kc, K / 64)); a0[c] = *(const bf16x8*)(ab + pg8::img_off(arow, kc, K / 64)); a1[c] = *(const bf16x8*)(ab + pg8::img_off(arow + 32, kc, K / 64)); }
; #pragma unroll
;         for (int c = 0; c < CH; ++c) { acc0 = __builtin_amdgcn_mfma_f32_32x32x16_bf16(bf[c], a0[c], acc0, 0, 0, 0); acc1 = __builtin_amdgcn_mfma_f32_32x32x16_bf16(bf[c], a1[c], acc1, 0, 0, 0); }
.LBB0_1434:
	v_add_u32_e32 v32, 0xffffff60, v51
	v_add_u32_e32 v52, 0xffffff70, v51
	v_add_u32_e32 v53, 0xffffff80, v51
	v_add_u32_e32 v54, 0xffffff90, v51
	v_add_u32_e32 v55, 0xffffffa0, v51
	v_add_u32_e32 v56, 0xffffffb0, v51
	v_subrev_u32_e32 v57, 64, v51
	v_subrev_u32_e32 v58, 48, v51
	v_subrev_u32_e32 v59, 32, v51
	v_add_u32_e32 v60, -16, v51
	v_ashrrev_i32_e32 v61, 6, v51
	v_ashrrev_i32_e32 v64, 6, v32
	v_bfe_u32 v62, v51, 5, 1
	v_lshlrev_b32_e32 v63, 1, v51
	v_bfe_u32 v65, v32, 5, 1
	v_lshlrev_b32_e32 v32, 1, v32
	v_ashrrev_i32_e32 v66, 6, v52
	v_bfe_u32 v67, v52, 5, 1
	v_lshlrev_b32_e32 v68, 1, v52
	v_ashrrev_i32_e32 v69, 6, v53
	v_bfe_u32 v70, v53, 5, 1
	v_lshlrev_b32_e32 v53, 1, v53
	v_ashrrev_i32_e32 v71, 6, v54
	v_bfe_u32 v72, v54, 5, 1
	v_lshlrev_b32_e32 v73, 1, v54
	v_ashrrev_i32_e32 v74, 6, v55
	v_bfe_u32 v75, v55, 5, 1
	v_lshlrev_b32_e32 v55, 1, v55
	v_ashrrev_i32_e32 v77, 6, v56
	v_bfe_u32 v79, v56, 5, 1
	v_lshlrev_b32_e32 v78, 1, v56
	v_ashrrev_i32_e32 v81, 6, v57
	v_bfe_u32 v83, v57, 5, 1
	v_lshlrev_b32_e32 v57, 1, v57
	v_ashrrev_i32_e32 v85, 6, v58
	v_lshlrev_b32_e32 v86, 1, v58
	v_ashrrev_i32_e32 v89, 6, v59
	v_ashrrev_i32_e32 v93, 6, v60
	v_lshlrev_b32_e32 v94, 1, v60
	v_add_u32_e32 v52, s8, v61
	v_add_u32_e32 v54, s9, v61
	v_add_u32_e32 v56, s8, v64
	v_bfe_u32 v87, v58, 5, 1
	v_bfe_u32 v91, v59, 5, 1
	v_lshlrev_b32_e32 v59, 1, v59
	v_bfe_u32 v95, v60, 5, 1
	v_or_b32_e32 v96, v62, v46
	v_and_b32_e32 v63, 48, v63
	v_or_b32_e32 v61, v62, v48
	v_or_b32_e32 v97, v62, v49
	v_or_b32_e32 v98, v65, v46
	v_and_b32_e32 v32, 48, v32
	v_add_u32_e32 v58, s9, v64
	v_or_b32_e32 v99, v65, v48
	v_or_b32_e32 v65, v65, v49
	v_add_u32_e32 v60, s8, v66
	v_or_b32_e32 v100, v67, v46
	v_and_b32_e32 v101, 48, v68
	v_add_u32_e32 v62, s9, v66
	v_or_b32_e32 v102, v67, v48
	v_or_b32_e32 v67, v67, v49
	v_add_u32_e32 v64, s8, v69
	v_or_b32_e32 v103, v70, v46
	v_and_b32_e32 v104, 48, v53
	v_add_u32_e32 v66, s9, v69
	v_or_b32_e32 v69, v70, v48
	v_or_b32_e32 v105, v70, v49
	v_add_u32_e32 v68, s8, v71
	v_or_b32_e32 v106, v72, v46
	v_and_b32_e32 v73, 48, v73
	v_add_u32_e32 v70, s9, v71
	v_or_b32_e32 v107, v72, v48
	v_or_b32_e32 v108, v72, v49
	v_add_u32_e32 v72, s8, v74
	v_and_b32_e32 v110, 48, v55
	v_add_u32_e32 v74, s9, v74
	v_add_u32_e32 v76, s8, v77
	v_and_b32_e32 v114, 48, v78
	v_add_u32_e32 v78, s9, v77
	v_add_u32_e32 v80, s8, v81
	v_and_b32_e32 v118, 48, v57
	v_add_u32_e32 v82, s9, v81
	v_add_u32_e32 v84, s8, v85
	v_and_b32_e32 v122, 48, v86
	v_add_u32_e32 v86, s9, v85
	v_add_u32_e32 v88, s8, v89
	v_add_u32_e32 v90, s9, v89
	v_add_u32_e32 v92, s8, v93
	v_and_b32_e32 v130, 48, v94
	v_add_u32_e32 v94, s9, v93
	v_ashrrev_i32_e32 v53, 31, v52
	v_ashrrev_i32_e32 v55, 31, v54
	v_ashrrev_i32_e32 v57, 31, v56
	v_or_b32_e32 v109, v75, v46
	v_or_b32_e32 v111, v75, v48
	v_or_b32_e32 v112, v75, v49
	v_or_b32_e32 v113, v79, v46
	v_or_b32_e32 v115, v79, v48
	v_or_b32_e32 v116, v79, v49
	v_or_b32_e32 v117, v83, v46
	v_or_b32_e32 v119, v83, v48
	v_or_b32_e32 v120, v83, v49
	v_or_b32_e32 v121, v87, v46
	v_or_b32_e32 v123, v87, v48
	v_or_b32_e32 v124, v87, v49
	v_or_b32_e32 v125, v91, v46
	v_and_b32_e32 v126, 48, v59
	v_or_b32_e32 v127, v91, v48
	v_or_b32_e32 v128, v91, v49
	v_or_b32_e32 v129, v95, v46
	v_or_b32_e32 v131, v95, v48
	v_or_b32_e32 v132, v95, v49
	v_or_b32_e32 v133, v63, v47
	v_lshlrev_b32_e32 v134, 10, v96
	v_or_b32_e32 v135, v63, v43
	v_lshlrev_b32_e32 v136, 10, v61
	v_lshlrev_b32_e32 v137, 10, v97
	v_or_b32_e32 v138, v32, v47
	v_lshlrev_b32_e32 v98, 10, v98
	v_ashrrev_i32_e32 v59, 31, v58
	v_lshlrev_b32_e32 v141, 10, v65
	v_ashrrev_i32_e32 v61, 31, v60
	v_ashrrev_i32_e32 v63, 31, v62
	v_lshlrev_b32_e32 v146, 10, v67
	v_ashrrev_i32_e32 v65, 31, v64
	v_ashrrev_i32_e32 v67, 31, v66
	v_lshlrev_b32_e32 v150, 10, v69
	v_ashrrev_i32_e32 v69, 31, v68
	v_or_b32_e32 v152, v73, v47
	v_ashrrev_i32_e32 v71, 31, v70
	v_or_b32_e32 v154, v73, v43
	v_ashrrev_i32_e32 v73, 31, v72
	v_ashrrev_i32_e32 v75, 31, v74
	v_ashrrev_i32_e32 v77, 31, v76
	v_ashrrev_i32_e32 v79, 31, v78
	v_ashrrev_i32_e32 v81, 31, v80
	v_ashrrev_i32_e32 v83, 31, v82
	v_ashrrev_i32_e32 v85, 31, v84
	v_ashrrev_i32_e32 v87, 31, v86
	v_ashrrev_i32_e32 v89, 31, v88
	v_ashrrev_i32_e32 v91, 31, v90
	v_ashrrev_i32_e32 v93, 31, v92
	v_ashrrev_i32_e32 v95, 31, v94
	v_lshlrev_b64 v[52:53], 14, v[52:53]
	v_lshlrev_b64 v[96:97], 14, v[54:55]
	v_lshlrev_b64 v[54:55], 14, v[56:57]
	v_or_b32_e32 v139, v32, v43
	v_bitop3_b32 v32, v138, v98, v37 bitop3:0xde
	v_lshlrev_b64 v[56:57], 14, v[58:59]
	v_lshlrev_b64 v[58:59], 14, v[60:61]
	v_lshlrev_b64 v[60:61], 14, v[62:63]
	v_lshlrev_b64 v[62:63], 14, v[64:65]
	v_lshlrev_b64 v[64:65], 14, v[66:67]
	v_lshlrev_b64 v[66:67], 14, v[68:69]
	v_lshlrev_b64 v[68:69], 14, v[70:71]
	v_lshlrev_b64 v[70:71], 14, v[72:73]
	v_lshlrev_b64 v[72:73], 14, v[74:75]
	v_lshlrev_b64 v[74:75], 14, v[76:77]
	v_lshlrev_b64 v[76:77], 14, v[78:79]
	v_lshlrev_b64 v[78:79], 14, v[80:81]
	v_lshlrev_b64 v[80:81], 14, v[82:83]
	v_lshlrev_b64 v[82:83], 14, v[84:85]
	v_lshlrev_b64 v[84:85], 14, v[86:87]
	v_lshlrev_b64 v[86:87], 14, v[88:89]
	v_lshlrev_b64 v[88:89], 14, v[90:91]
	v_lshlrev_b64 v[90:91], 14, v[92:93]
	v_lshlrev_b64 v[92:93], 14, v[94:95]
	v_lshl_add_u64 v[94:95], s[6:7], 0, v[52:53]
	v_lshl_add_u64 v[52:53], s[6:7], 0, v[54:55]
	v_lshl_add_u64 v[52:53], v[52:53], 0, v[32:33]
	global_load_dwordx4 v[164:167], v[52:53], off
	v_lshlrev_b32_e32 v140, 10, v99
	v_lshl_add_u64 v[98:99], s[4:5], 0, v[56:57]
	v_bitop3_b32 v32, v139, v140, v44 bitop3:0xde
	v_lshl_add_u64 v[56:57], v[98:99], 0, v[32:33]
	v_or_b32_e32 v142, v101, v47
	v_lshlrev_b32_e32 v143, 10, v100
	v_or_b32_e32 v144, v101, v43
; __host__ __device__ __forceinline__ size_t img_off(int row, int col, int nkt) { return ((size_t)((row >> 7) * nkt + (col >> 6)) << 14) + (size_t)lds_byte(row & 127, col & 63); }
; __host__ __device__ __forceinline__ size_t img_off_b(int row, int col, int nkt) { return img_off((row & ~31) | invperm32(row & 31), col, nkt); }
; template <int K, int MODE>
; __device__ __forceinline__ void skinny_tile(Frame& F, const Args& A, const bf16* Am  , const bf16* Bt  ) {
;     ...
;     for (int k0 = 0; k0 < NK; k0 += CH) {
;         bf16x8 bf[CH], a0[CH], a1[CH];
; #pragma unroll
;         for (int c = 0; c < CH; ++c) { const int kc = kc0 + 16 * (k0 + c); bf[c] = *(const bf16x8*)(bb + pg8::img_off_b(brow, kc, K / 64)); a0[c] = *(const bf16x8*)(ab + pg8::img_off(arow, kc, K / 64)); a1[c] = *(const bf16x8*)(ab + pg8::img_off(arow + 32, kc, K / 64)); }
; #pragma unroll
;         for (int c = 0; c < CH; ++c) { acc0 = __builtin_amdgcn_mfma_f32_32x32x16_bf16(bf[c], a0[c], acc0, 0, 0, 0); acc1 = __builtin_amdgcn_mfma_f32_32x32x16_bf16(bf[c], a1[c], acc1, 0, 0, 0); }
	v_lshl_add_u64 v[100:101], s[6:7], 0, v[58:59]
	global_load_dwordx4 v[168:171], v[56:57], off
	v_bitop3_b32 v32, v139, v141, v44 bitop3:0xde
	v_lshlrev_b32_e32 v145, 10, v102
	v_lshlrev_b32_e32 v148, 10, v103
	v_lshl_add_u64 v[102:103], s[4:5], 0, v[60:61]
	v_lshl_add_u64 v[60:61], v[98:99], 0, v[32:33]
	v_or_b32_e32 v147, v104, v47
	v_or_b32_e32 v149, v104, v43
	v_lshlrev_b32_e32 v151, 10, v105
	v_lshl_add_u64 v[104:105], s[6:7], 0, v[62:63]
	global_load_dwordx4 v[172:175], v[60:61], off
	v_bitop3_b32 v32, v142, v143, v37 bitop3:0xde
	v_lshlrev_b32_e32 v153, 10, v106
	v_lshlrev_b32_e32 v155, 10, v107
	v_lshl_add_u64 v[106:107], s[4:5], 0, v[64:65]
	v_lshl_add_u64 v[64:65], v[100:101], 0, v[32:33]
	v_lshlrev_b32_e32 v156, 10, v108
	v_lshlrev_b32_e32 v158, 10, v109
	v_lshl_add_u64 v[108:109], s[6:7], 0, v[66:67]
	global_load_dwordx4 v[176:179], v[64:65], off
	v_bitop3_b32 v32, v144, v145, v44 bitop3:0xde
	v_lshl_add_u64 v[98:99], v[102:103], 0, v[32:33]
	global_load_dwordx4 v[180:183], v[98:99], off
	v_bitop3_b32 v32, v144, v146, v44 bitop3:0xde
	v_lshl_add_u64 v[98:99], v[102:103], 0, v[32:33]
	v_bitop3_b32 v32, v147, v148, v37 bitop3:0xde
	v_lshl_add_u64 v[68:69], s[4:5], 0, v[68:69]
	v_or_b32_e32 v157, v110, v47
	v_lshl_add_u64 v[70:71], s[6:7], 0, v[70:71]
	global_load_dwordx4 v[184:187], v[98:99], off
	v_lshl_add_u64 v[60:61], v[104:105], 0, v[32:33]
	global_load_dwordx4 v[188:191], v[60:61], off
	v_bitop3_b32 v32, v149, v150, v44 bitop3:0xde
	v_lshl_add_u64 v[98:99], v[106:107], 0, v[32:33]
	v_bitop3_b32 v32, v149, v151, v44 bitop3:0xde
	v_or_b32_e32 v110, v110, v43
	global_load_dwordx4 v[192:195], v[98:99], off
	v_lshl_add_u64 v[98:99], v[106:107], 0, v[32:33]
	v_bitop3_b32 v32, v152, v153, v37 bitop3:0xde
	v_lshlrev_b32_e32 v111, 10, v111
	v_lshl_add_u64 v[72:73], s[4:5], 0, v[72:73]
	v_lshlrev_b32_e32 v112, 10, v112
	v_or_b32_e32 v159, v114, v47
	global_load_dwordx4 v[196:199], v[98:99], off
	v_lshl_add_u64 v[64:65], v[108:109], 0, v[32:33]
	global_load_dwordx4 v[202:205], v[64:65], off
	v_bitop3_b32 v32, v154, v155, v44 bitop3:0xde
	v_lshl_add_u64 v[98:99], v[68:69], 0, v[32:33]
	v_bitop3_b32 v32, v154, v156, v44 bitop3:0xde
	v_lshl_add_u64 v[68:69], v[68:69], 0, v[32:33]
	global_load_dwordx4 v[206:209], v[98:99], off
	v_bitop3_b32 v32, v157, v158, v37 bitop3:0xde
	v_lshlrev_b32_e32 v113, 10, v113
	v_lshl_add_u64 v[74:75], s[6:7], 0, v[74:75]
	v_or_b32_e32 v114, v114, v43
	v_lshlrev_b32_e32 v115, 10, v115
	v_lshl_add_u64 v[76:77], s[4:5], 0, v[76:77]
	global_load_dwordx4 v[210:213], v[68:69], off
	v_lshl_add_u64 v[60:61], v[70:71], 0, v[32:33]
	global_load_dwordx4 v[214:217], v[60:61], off
	v_bitop3_b32 v32, v110, v111, v44 bitop3:0xde
	v_lshl_add_u64 v[68:69], v[72:73], 0, v[32:33]
	v_bitop3_b32 v32, v110, v112, v44 bitop3:0xde
	v_lshlrev_b32_e32 v116, 10, v116
	global_load_dwordx4 v[218:221], v[68:69], off
	v_lshl_add_u64 v[68:69], v[72:73], 0, v[32:33]
	v_bitop3_b32 v32, v159, v113, v37 bitop3:0xde
	v_or_b32_e32 v160, v118, v47
	v_lshlrev_b32_e32 v117, 10, v117
	v_lshl_add_u64 v[78:79], s[6:7], 0, v[78:79]
	v_or_b32_e32 v118, v118, v43
	global_load_dwordx4 v[222:225], v[68:69], off
	v_lshl_add_u64 v[64:65], v[74:75], 0, v[32:33]
	global_load_dwordx4 v[226:229], v[64:65], off
	v_bitop3_b32 v32, v114, v115, v44 bitop3:0xde
	v_lshl_add_u64 v[68:69], v[76:77], 0, v[32:33]
	v_bitop3_b32 v32, v114, v116, v44 bitop3:0xde
	v_lshlrev_b32_e32 v119, 10, v119
	global_load_dwordx4 v[230:233], v[68:69], off
	v_lshl_add_u64 v[68:69], v[76:77], 0, v[32:33]
	v_bitop3_b32 v32, v160, v117, v37 bitop3:0xde
	v_lshl_add_u64 v[80:81], s[4:5], 0, v[80:81]
	v_lshlrev_b32_e32 v120, 10, v120
	v_or_b32_e32 v161, v122, v47
	v_lshlrev_b32_e32 v121, 10, v121
	global_load_dwordx4 v[234:237], v[68:69], off
	v_lshl_add_u64 v[60:61], v[78:79], 0, v[32:33]
	global_load_dwordx4 v[238:241], v[60:61], off
	v_bitop3_b32 v32, v118, v119, v44 bitop3:0xde
	v_lshl_add_u64 v[68:69], v[80:81], 0, v[32:33]
	v_bitop3_b32 v32, v118, v120, v44 bitop3:0xde
	v_lshl_add_u64 v[82:83], s[6:7], 0, v[82:83]
	global_load_dwordx4 v[242:245], v[68:69], off
	v_lshl_add_u64 v[68:69], v[80:81], 0, v[32:33]
	v_bitop3_b32 v32, v161, v121, v37 bitop3:0xde
	v_or_b32_e32 v122, v122, v43
	v_lshlrev_b32_e32 v123, 10, v123
	v_lshl_add_u64 v[84:85], s[4:5], 0, v[84:85]
	v_lshlrev_b32_e32 v124, 10, v124
	global_load_dwordx4 v[246:249], v[68:69], off
	v_lshl_add_u64 v[64:65], v[82:83], 0, v[32:33]
	s_waitcnt vmcnt(19)
	v_mfma_f32_32x32x16_bf16 v[0:15], v[164:167], v[168:171], v[0:15]
	global_load_dwordx4 v[168:171], v[64:65], off
	v_bitop3_b32 v32, v122, v123, v44 bitop3:0xde
	v_lshl_add_u64 v[68:69], v[84:85], 0, v[32:33]
	v_bitop3_b32 v32, v122, v124, v44 bitop3:0xde
	v_or_b32_e32 v162, v126, v47
	s_waitcnt vmcnt(19)
	v_mfma_f32_32x32x16_bf16 v[16:31], v[164:167], v[172:175], v[16:31]
	global_load_dwordx4 v[164:167], v[68:69], off
	v_lshl_add_u64 v[68:69], v[84:85], 0, v[32:33]
	v_lshlrev_b32_e32 v125, 10, v125
	v_lshl_add_u64 v[86:87], s[6:7], 0, v[86:87]
	v_bitop3_b32 v32, v162, v125, v37 bitop3:0xde
	v_or_b32_e32 v126, v126, v43
	v_lshlrev_b32_e32 v127, 10, v127
	global_load_dwordx4 v[172:175], v[68:69], off
	v_lshl_add_u64 v[60:61], v[86:87], 0, v[32:33]
	s_waitcnt vmcnt(19)
	v_mfma_f32_32x32x16_bf16 v[0:15], v[176:179], v[180:183], v[0:15]
	global_load_dwordx4 v[180:183], v[60:61], off
	v_lshl_add_u64 v[88:89], s[4:5], 0, v[88:89]
	v_bitop3_b32 v32, v126, v127, v44 bitop3:0xde
	v_lshl_add_u64 v[68:69], v[88:89], 0, v[32:33]
	v_lshlrev_b32_e32 v128, 10, v128
	s_waitcnt vmcnt(19)
; __host__ __device__ __forceinline__ size_t img_off(int row, int col, int nkt) { return ((size_t)((row >> 7) * nkt + (col >> 6)) << 14) + (size_t)lds_byte(row & 127, col & 63); }
; __host__ __device__ __forceinline__ size_t img_off_b(int row, int col, int nkt) { return img_off((row & ~31) | invperm32(row & 31), col, nkt); }
; template <int K, int MODE>
; __device__ __forceinline__ void skinny_tile(Frame& F, const Args& A, const bf16* Am  , const bf16* Bt  ) {
;     ...
;     for (int k0 = 0; k0 < NK; k0 += CH) {
;         bf16x8 bf[CH], a0[CH], a1[CH];
; #pragma unroll
;         for (int c = 0; c < CH; ++c) { const int kc = kc0 + 16 * (k0 + c); bf[c] = *(const bf16x8*)(bb + pg8::img_off_b(brow, kc, K / 64)); a0[c] = *(const bf16x8*)(ab + pg8::img_off(arow, kc, K / 64)); a1[c] = *(const bf16x8*)(ab + pg8::img_off(arow + 32, kc, K / 64)); }
; #pragma unroll
;         for (int c = 0; c < CH; ++c) { acc0 = __builtin_amdgcn_mfma_f32_32x32x16_bf16(bf[c], a0[c], acc0, 0, 0, 0); acc1 = __builtin_amdgcn_mfma_f32_32x32x16_bf16(bf[c], a1[c], acc1, 0, 0, 0); }
;     }
	v_mfma_f32_32x32x16_bf16 v[16:31], v[176:179], v[184:187], v[16:31]
	global_load_dwordx4 v[184:187], v[68:69], off
	v_bitop3_b32 v32, v126, v128, v44 bitop3:0xde
	v_lshl_add_u64 v[68:69], v[88:89], 0, v[32:33]
	v_or_b32_e32 v163, v130, v47
	v_lshlrev_b32_e32 v129, 10, v129
	v_lshl_add_u64 v[90:91], s[6:7], 0, v[90:91]
	v_bitop3_b32 v32, v163, v129, v37 bitop3:0xde
	global_load_dwordx4 v[176:179], v[68:69], off
	v_lshl_add_u64 v[64:65], v[90:91], 0, v[32:33]
	s_waitcnt vmcnt(19)
	v_mfma_f32_32x32x16_bf16 v[0:15], v[188:191], v[192:195], v[0:15]
	global_load_dwordx4 v[192:195], v[64:65], off
	v_or_b32_e32 v130, v130, v43
	v_lshlrev_b32_e32 v131, 10, v131
	v_lshl_add_u64 v[92:93], s[4:5], 0, v[92:93]
	v_bitop3_b32 v32, v130, v131, v44 bitop3:0xde
	v_lshl_add_u64 v[68:69], v[92:93], 0, v[32:33]
	s_waitcnt vmcnt(19)
	v_mfma_f32_32x32x16_bf16 v[16:31], v[188:191], v[196:199], v[16:31]
	global_load_dwordx4 v[196:199], v[68:69], off
	v_lshlrev_b32_e32 v132, 10, v132
	v_bitop3_b32 v32, v130, v132, v44 bitop3:0xde
	v_lshl_add_u64 v[68:69], v[92:93], 0, v[32:33]
	v_bitop3_b32 v32, v133, v134, v37 bitop3:0xde
	v_add_co_u32_e32 v50, vcc, 11, v50
	global_load_dwordx4 v[188:191], v[68:69], off
	v_lshl_add_u64 v[60:61], s[4:5], 0, v[96:97]
	s_andn2_b64 vcc, exec, vcc
	v_add_u32_e32 v51, 0xb0, v51
	v_lshl_add_u64 v[56:57], v[94:95], 0, v[32:33]
	s_waitcnt vmcnt(19)
	v_mfma_f32_32x32x16_bf16 v[0:15], v[202:205], v[206:209], v[0:15]
	global_load_dwordx4 v[206:209], v[56:57], off
	v_bitop3_b32 v32, v135, v136, v44 bitop3:0xde
	v_lshl_add_u64 v[62:63], v[60:61], 0, v[32:33]
	v_bitop3_b32 v32, v135, v137, v44 bitop3:0xde
	v_lshl_add_u64 v[60:61], v[60:61], 0, v[32:33]
	s_waitcnt vmcnt(19)
	v_mfma_f32_32x32x16_bf16 v[16:31], v[202:205], v[210:213], v[16:31]
	global_load_dwordx4 v[210:213], v[62:63], off
	global_load_dwordx4 v[202:205], v[60:61], off
	s_waitcnt vmcnt(19)
	v_mfma_f32_32x32x16_bf16 v[0:15], v[214:217], v[218:221], v[0:15]
	s_waitcnt vmcnt(18)
	v_mfma_f32_32x32x16_bf16 v[16:31], v[214:217], v[222:225], v[16:31]
	s_waitcnt vmcnt(16)
	v_mfma_f32_32x32x16_bf16 v[0:15], v[226:229], v[230:233], v[0:15]
	s_waitcnt vmcnt(15)
	v_mfma_f32_32x32x16_bf16 v[16:31], v[226:229], v[234:237], v[16:31]
	s_waitcnt vmcnt(13)
	v_mfma_f32_32x32x16_bf16 v[0:15], v[238:241], v[242:245], v[0:15]
	s_waitcnt vmcnt(12)
	v_mfma_f32_32x32x16_bf16 v[16:31], v[238:241], v[246:249], v[16:31]
	s_waitcnt vmcnt(10)
	v_mfma_f32_32x32x16_bf16 v[0:15], v[168:171], v[164:167], v[0:15]
	s_waitcnt vmcnt(9)
	v_mfma_f32_32x32x16_bf16 v[16:31], v[168:171], v[172:175], v[16:31]
	s_waitcnt vmcnt(7)
	v_mfma_f32_32x32x16_bf16 v[0:15], v[180:183], v[184:187], v[0:15]
	s_waitcnt vmcnt(6)
	v_mfma_f32_32x32x16_bf16 v[16:31], v[180:183], v[176:179], v[16:31]
	s_waitcnt vmcnt(4)
	v_mfma_f32_32x32x16_bf16 v[0:15], v[192:195], v[196:199], v[0:15]
	s_waitcnt vmcnt(3)
	v_mfma_f32_32x32x16_bf16 v[16:31], v[192:195], v[188:191], v[16:31]
	s_waitcnt vmcnt(1)
	v_mfma_f32_32x32x16_bf16 v[0:15], v[206:209], v[210:213], v[0:15]
	s_nop 1
	s_waitcnt vmcnt(0)
	v_mfma_f32_32x32x16_bf16 v[16:31], v[206:209], v[202:205], v[16:31]
	s_cbranch_vccz .LBB0_1434
; __host__ __device__ __forceinline__ size_t img_off(int row, int col, int nkt) { return ((size_t)((row >> 7) * nkt + (col >> 6)) << 14) + (size_t)lds_byte(row & 127, col & 63); }
; #define LAS __attribute__((address_space(3)))
; __device__ __forceinline__ unsigned pk2(float lo, float hi) { return pg8::cvt_pk_bf16(lo, hi); }
; template <int K, int MODE>
; __device__ __forceinline__ void skinny_tile(Frame& F, const Args& A, const bf16* Am  , const bf16* Bt  ) {
;     ...
;     LAS float* red = (LAS float*)(F.lds + RING_OFF);
; #pragma unroll
;     for (int q = 0; q < 16; ++q) { red[((w * 2 + 0) * 16 + q) * 64 + lane] = acc0[q]; red[((w * 2 + 1) * 16 + q) * 64 + lane] = acc1[q]; }
;     __syncthreads();
;     const int rb = w >> 2, qg = w & 3;
;     f32x4 v = (f32x4){0.f, 0.f, 0.f, 0.f};
; #pragma unroll
;     for (int ww = 0; ww < 8; ++ww)
; #pragma unroll
;         for (int j = 0; j < 4; ++j) v[j] += red[((ww * 2 + rb) * 16 + 4 * qg + j) * 64 + lane];
;     const int srow = r0 + 32 * rb + il, col = c0 + 8 * qg + 4 * hi;
;     float* yp = F.out + O_Y + (size_t)(MP + srow) * DM + col;
;     if (MODE == 0) {
;         const f32x4 x = *(const f32x4*)(A.in[1] + (size_t)srow * DM + col); v = v + x;
;         v2u o; o.x = pk2(v[0], v[1]); o.y = pk2(v[2], v[3]); *(v2u*)((char*)(F.ws + WS_X1B) + pg8::img_off(MP + srow, col, DM / 64)) = o;
;         float s = (v[0] * v[0] + v[1] * v[1]) + (v[2] * v[2] + v[3] * v[3]); s += __shfl_xor(s, 32);
;         if (hi == 0) atomicAdd((float*)F.ws + CW_SS + MP + srow, s);
;     } else {
;         const v2u xb = *(const v2u*)((const char*)(F.ws + WS_X1B) + pg8::img_off(MP + srow, col, DM / 64)); *(f32x4*)yp = v + (f32x4){bf_lo(xb.x), bf_hi(xb.x), bf_lo(xb.y), bf_hi(xb.y)};
;     }
;     __syncthreads();
	s_nop 7
	ds_write2st64_b32 v40, v0, v1 offset1:1
	s_nop 1
	ds_write2st64_b32 v40, v16, v17 offset0:16 offset1:17
	ds_write2st64_b32 v40, v2, v3 offset0:2 offset1:3
	ds_write2st64_b32 v40, v18, v19 offset0:18 offset1:19
	ds_write2st64_b32 v40, v4, v5 offset0:4 offset1:5
	ds_write2st64_b32 v40, v20, v21 offset0:20 offset1:21
	ds_write2st64_b32 v40, v6, v7 offset0:6 offset1:7
	ds_write2st64_b32 v40, v22, v23 offset0:22 offset1:23
	ds_write2st64_b32 v40, v8, v9 offset0:8 offset1:9
	ds_write2st64_b32 v40, v24, v25 offset0:24 offset1:25
	ds_write2st64_b32 v40, v10, v11 offset0:10 offset1:11
	ds_write2st64_b32 v40, v26, v27 offset0:26 offset1:27
	ds_write2st64_b32 v40, v12, v13 offset0:12 offset1:13
	ds_write2st64_b32 v40, v28, v29 offset0:28 offset1:29
	ds_write2st64_b32 v40, v14, v15 offset0:14 offset1:15
	ds_write2st64_b32 v40, v30, v31 offset0:30 offset1:31
	v_add_u32_e32 v1, s2, v38
	v_add_u32_e32 v2, 0x4000, v1
	v_add_u32_e32 v0, s3, v39
	v_ashrrev_i32_e32 v3, 3, v2
	v_and_b32_e32 v3, -16, v3
	v_ashrrev_i32_e32 v4, 6, v0
	v_lshrrev_b32_e32 v1, 3, v1
	v_add_u32_e32 v4, v3, v4
	v_and_b32_e32 v1, 14, v1
	v_lshrrev_b32_e32 v3, 5, v0
	v_and_or_b32 v1, v3, 1, v1
	v_lshlrev_b32_e32 v3, 6, v2
	v_and_b32_e32 v3, 0x3c0, v3
	v_lshlrev_b32_e32 v6, 1, v0
	v_ashrrev_i32_e32 v5, 31, v4
	v_and_or_b32 v3, v6, 56, v3
	v_lshlrev_b32_e32 v6, 2, v2
	v_lshlrev_b64 v[4:5], 14, v[4:5]
	v_lshlrev_b32_e32 v1, 10, v1
	v_and_b32_e32 v6, 32, v6
	v_bitop3_b32 v32, v3, v1, v6 bitop3:0xde
	v_lshl_add_u64 v[4:5], s[0:1], 0, v[4:5]
	v_lshl_add_u64 v[4:5], v[4:5], 0, v[32:33]
	s_waitcnt lgkmcnt(0)
	s_barrier
	global_load_dwordx2 v[4:5], v[4:5], off
	v_ashrrev_i32_e32 v3, 31, v2
	v_readlane_b32 s8, v251, 6
	ds_read2st64_b32 v[6:7], v45 offset1:1
	ds_read2st64_b32 v[8:9], v45 offset0:2 offset1:3
	ds_read2st64_b32 v[10:11], v45 offset0:32 offset1:33
	ds_read2st64_b32 v[12:13], v45 offset0:34 offset1:35
	ds_read2st64_b32 v[14:15], v45 offset0:64 offset1:65
	ds_read2st64_b32 v[16:17], v45 offset0:66 offset1:67
	ds_read2st64_b32 v[18:19], v45 offset0:96 offset1:97
	ds_read2st64_b32 v[20:21], v45 offset0:98 offset1:99
	ds_read2st64_b32 v[22:23], v45 offset0:128 offset1:129
	ds_read2st64_b32 v[24:25], v45 offset0:130 offset1:131
	ds_read2st64_b32 v[26:27], v45 offset0:160 offset1:161
	ds_read2st64_b32 v[28:29], v45 offset0:162 offset1:163
	ds_read2st64_b32 v[30:31], v45 offset0:192 offset1:193
	ds_read2st64_b32 v[46:47], v45 offset0:194 offset1:195
	ds_read2st64_b32 v[48:49], v45 offset0:224 offset1:225
	ds_read2st64_b32 v[50:51], v45 offset0:226 offset1:227
	v_lshlrev_b64 v[2:3], 12, v[2:3]
	v_readlane_b32 s14, v251, 12
	v_readlane_b32 s15, v251, 13
	v_ashrrev_i32_e32 v1, 31, v0
	s_waitcnt lgkmcnt(14)
	v_pk_add_f32 v[8:9], v[8:9], 0 op_sel_hi:[1,0]
	v_lshl_add_u64 v[2:3], s[14:15], 0, v[2:3]
	v_pk_add_f32 v[6:7], v[6:7], 0 op_sel_hi:[1,0]
	v_lshl_add_u64 v[52:53], v[0:1], 2, v[2:3]
	s_waitcnt lgkmcnt(13)
	v_pk_add_f32 v[0:1], v[6:7], v[10:11]
	s_waitcnt lgkmcnt(12)
	v_pk_add_f32 v[2:3], v[8:9], v[12:13]
	s_waitcnt lgkmcnt(11)
	v_pk_add_f32 v[0:1], v[0:1], v[14:15]
	s_waitcnt lgkmcnt(10)
	v_pk_add_f32 v[2:3], v[2:3], v[16:17]
	s_waitcnt lgkmcnt(9)
	v_pk_add_f32 v[0:1], v[0:1], v[18:19]
	s_waitcnt lgkmcnt(8)
	v_pk_add_f32 v[2:3], v[2:3], v[20:21]
	s_waitcnt lgkmcnt(7)
	v_pk_add_f32 v[0:1], v[0:1], v[22:23]
	s_waitcnt lgkmcnt(6)
	v_pk_add_f32 v[2:3], v[2:3], v[24:25]
	s_waitcnt lgkmcnt(5)
	v_pk_add_f32 v[0:1], v[0:1], v[26:27]
	s_waitcnt lgkmcnt(4)
	v_pk_add_f32 v[2:3], v[2:3], v[28:29]
	v_readlane_b32 s2, v251, 3
	s_waitcnt lgkmcnt(2)
	v_pk_add_f32 v[2:3], v[2:3], v[46:47]
	v_pk_add_f32 v[0:1], v[0:1], v[30:31]
	s_add_i32 s96, s96, s2
	s_waitcnt lgkmcnt(1)
	v_pk_add_f32 v[0:1], v[0:1], v[48:49]
	s_waitcnt lgkmcnt(0)
	v_pk_add_f32 v[2:3], v[2:3], v[50:51]
	s_cmpk_gt_i32 s96, 0xff
	v_readlane_b32 s9, v251, 7
	v_readlane_b32 s10, v251, 8
	v_readlane_b32 s11, v251, 9
	v_readlane_b32 s12, v251, 10
	v_readlane_b32 s13, v251, 11
	s_waitcnt vmcnt(0)
	v_lshlrev_b32_e32 v6, 16, v4
	v_and_b32_e32 v7, 0xffff0000, v4
	v_lshlrev_b32_e32 v4, 16, v5
	v_and_b32_e32 v5, 0xffff0000, v5
	v_pk_add_f32 v[2:3], v[2:3], v[4:5]
	v_pk_add_f32 v[0:1], v[0:1], v[6:7]
	global_store_dwordx4 v[52:53], v[0:3], off
	s_barrier
	s_cbranch_scc0 .LBB0_1433

; __global__ void __launch_bounds__(NWAVES * 64, 2) hymba_fwd(Args args) {
	.amdhsa_kernel _Z9hymba_fwd4Args
		.amdhsa_group_segment_fixed_size 0
		.amdhsa_private_segment_fixed_size 0
		.amdhsa_kernarg_size 432
		.amdhsa_user_sgpr_count 2
		.amdhsa_user_sgpr_dispatch_ptr 0
		.amdhsa_user_sgpr_queue_ptr 0
		.amdhsa_user_sgpr_kernarg_segment_ptr 1
		.amdhsa_user_sgpr_dispatch_id 0
		.amdhsa_user_sgpr_kernarg_preload_length 0
		.amdhsa_user_sgpr_kernarg_preload_offset 0
		.amdhsa_user_sgpr_private_segment_size 0
		.amdhsa_uses_dynamic_stack 0
		.amdhsa_enable_private_segment 0
		.amdhsa_system_sgpr_workgroup_id_x 1
		.amdhsa_system_sgpr_workgroup_id_y 0
		.amdhsa_system_sgpr_workgroup_id_z 0
		.amdhsa_system_sgpr_workgroup_info 0
		.amdhsa_system_vgpr_workitem_id 0
		.amdhsa_next_free_vgpr 252
		.amdhsa_next_free_sgpr 102
		.amdhsa_accum_offset 252
		.amdhsa_reserve_vcc 1
		.amdhsa_float_round_mode_32 0
		.amdhsa_float_round_mode_16_64 0
		.amdhsa_float_denorm_mode_32 3
		.amdhsa_float_denorm_mode_16_64 3
		.amdhsa_dx10_clamp 1
		.amdhsa_ieee_mode 1
		.amdhsa_fp16_overflow 0
		.amdhsa_tg_split 0
		.amdhsa_exception_fp_ieee_invalid_op 0
		.amdhsa_exception_fp_denorm_src 0
		.amdhsa_exception_fp_ieee_div_zero 0
		.amdhsa_exception_fp_ieee_overflow 0
		.amdhsa_exception_fp_ieee_underflow 0
		.amdhsa_exception_fp_ieee_inexact 0
		.amdhsa_exception_int_div_zero 0
	.end_amdhsa_kernel

; __global__ void __launch_bounds__(NWAVES * 64, 2) hymba_fwd(Args args) {
amdhsa.kernels:
  - .agpr_count:     0
    .args:
      - .offset:         0
        .size:           176
        .value_kind:     by_value
      - .offset:         176
        .size:           4
        .value_kind:     hidden_block_count_x
      - .offset:         180
        .size:           4
        .value_kind:     hidden_block_count_y
      - .offset:         184
        .size:           4
        .value_kind:     hidden_block_count_z
      - .offset:         188
        .size:           2
        .value_kind:     hidden_group_size_x
      - .offset:         190
        .size:           2
        .value_kind:     hidden_group_size_y
      - .offset:         192
        .size:           2
        .value_kind:     hidden_group_size_z
      - .offset:         194
        .size:           2
        .value_kind:     hidden_remainder_x
      - .offset:         196
        .size:           2
        .value_kind:     hidden_remainder_y
      - .offset:         198
        .size:           2
        .value_kind:     hidden_remainder_z
      - .offset:         216
        .size:           8
        .value_kind:     hidden_global_offset_x
      - .offset:         224
        .size:           8
        .value_kind:     hidden_global_offset_y
      - .offset:         232
        .size:           8
        .value_kind:     hidden_global_offset_z
      - .offset:         240
        .size:           2
        .value_kind:     hidden_grid_dims
      - .offset:         296
        .size:           4
        .value_kind:     hidden_dynamic_lds_size
    .group_segment_fixed_size: 0
    .kernarg_segment_align: 8
    .kernarg_segment_size: 432
    .language:       OpenCL C
    .language_version:
      - 2
      - 0
    .max_flat_workgroup_size: 512
    .name:           _Z9hymba_fwd4Args
    .private_segment_fixed_size: 0
    .sgpr_count:     108
    .sgpr_spill_count: 121
    .symbol:         _Z9hymba_fwd4Args.kd
    .uniform_work_group_size: 1
    .uses_dynamic_stack: false
    .vgpr_count:     252
    .vgpr_spill_count: 0
    .wavefront_size: 64
